# instruction selection in the P5 epilogue: the preloaded row statistics are consumed in place (sixteen register copies per wave removed), no setprio
# speedup vs baseline: 1.0029x; 1.0029x over previous
.LBB0_798:
	s_lshl_b32 s51, s36, 15
	s_lshl_b32 s4, s33, 11
	s_add_u32 s4, s14, s4
	s_addc_u32 s5, s15, 0
	s_mov_b64 s[36:37], s[4:5]
	v_pk_mul_f32 v[146:147], v[150:151], v[146:147]
	v_lshl_add_u64 v[152:153], s[36:37], 0, v[80:81]
	s_add_u32 s36, s4, 0x80
	s_addc_u32 s37, s5, 0
	v_pk_mul_f32 v[144:145], v[148:149], v[144:145]
	v_lshl_add_u64 v[152:153], s[36:37], 0, v[80:81]
	s_add_u32 s36, s4, 0x100
	s_addc_u32 s37, s5, 0
	s_mul_i32 s33, s33, 0x2c0000
	v_lshl_add_u64 v[152:153], s[36:37], 0, v[80:81]
	s_add_u32 s36, s4, 0x180
	s_addc_u32 s37, s5, 0
	v_pk_mul_f32 v[138:139], v[142:143], v[138:139]
	v_lshl_add_u64 v[152:153], s[36:37], 0, v[80:81]
	s_add_u32 s36, s4, 0x400
	s_addc_u32 s37, s5, 0
	v_pk_mul_f32 v[136:137], v[140:141], v[136:137]
	v_lshl_add_u64 v[152:153], s[36:37], 0, v[80:81]
	s_add_u32 s36, s4, 0x480
	s_addc_u32 s37, s5, 0
	v_pk_mul_f32 v[130:131], v[134:135], v[130:131]
	v_lshl_add_u64 v[152:153], s[36:37], 0, v[80:81]
	s_add_u32 s36, s4, 0x500
	s_addc_u32 s37, s5, 0
	s_add_u32 s4, s4, 0x580
	s_addc_u32 s5, s5, 0
	v_lshl_add_u64 v[152:153], s[36:37], 0, v[80:81]
	s_add_i32 s33, s33, s51
	v_lshl_add_u64 v[152:153], s[4:5], 0, v[80:81]
	s_add_u32 s4, s20, s33
	s_addc_u32 s5, s68, 0
	s_mov_b64 s[36:37], s[4:5]
	v_pk_mul_f32 v[128:129], v[132:133], v[128:129]
	v_pk_mul_f32 v[122:123], v[126:127], v[122:123]
	v_pk_mul_f32 v[120:121], v[124:125], v[120:121]
	s_add_u32 s4, s4, 0x800
	s_addc_u32 s5, s5, 0
	v_pk_mul_f32 v[114:115], v[118:119], v[114:115]
	v_pk_mul_f32 v[112:113], v[116:117], v[112:113]
	v_pk_mul_f32 v[106:107], v[110:111], v[106:107]
	v_pk_mul_f32 v[104:105], v[108:109], v[104:105]
	v_pk_mul_f32 v[74:75], v[78:79], v[74:75]
	v_pk_mul_f32 v[72:73], v[76:77], v[72:73]
	v_pk_mul_f32 v[66:67], v[70:71], v[66:67]
	v_pk_mul_f32 v[64:65], v[68:69], v[64:65]
	v_pk_mul_f32 v[58:59], v[62:63], v[58:59]
	v_pk_mul_f32 v[56:57], v[60:61], v[56:57]
	v_pk_mul_f32 v[50:51], v[54:55], v[50:51]
	v_pk_mul_f32 v[48:49], v[52:53], v[48:49]
	v_pk_mul_f32 v[42:43], v[46:47], v[42:43]
	v_pk_mul_f32 v[40:41], v[44:45], v[40:41]
	v_pk_mul_f32 v[34:35], v[38:39], v[34:35]
	v_pk_mul_f32 v[32:33], v[36:37], v[32:33]
	v_pk_mul_f32 v[26:27], v[30:31], v[26:27]
	v_pk_mul_f32 v[24:25], v[28:29], v[24:25]
	v_pk_mul_f32 v[18:19], v[22:23], v[18:19]
	v_pk_mul_f32 v[16:17], v[20:21], v[16:17]
	v_pk_mul_f32 v[10:11], v[14:15], v[10:11]
	v_pk_mul_f32 v[8:9], v[12:13], v[8:9]
	v_pk_mul_f32 v[2:3], v[6:7], v[2:3]
	v_pk_mul_f32 v[0:1], v[4:5], v[0:1]
	s_and_b64 vcc, exec, s[2:3]
	s_cbranch_vccz .Lab_p5
	s_barrier
.Lab_p5:
	s_nop 0
	v_cvt_f32_u32_e32 v171, v85
	v_cvt_f32_u32_e32 v170, v84
	v_fmac_f32_e32 v170, 0x4f800000, v171
	v_fmamk_f32 v170, v170, 0x30000000, v234
	v_rsq_f32_e32 v178, v170
	s_nop 0
	v_mul_f32_e32 v174, 0xbfb8aa3b, v178
	v_pk_mul_f32 v[172:173], v[150:151], v[174:175] op_sel_hi:[1,0]
	v_pk_mul_f32 v[170:171], v[148:149], v[174:175] op_sel_hi:[1,0]
	v_pk_mul_f32 v[176:177], v[142:143], v[174:175] op_sel_hi:[1,0]
	v_pk_mul_f32 v[174:175], v[140:141], v[174:175] op_sel_hi:[1,0]
	v_mul_f32_e32 v178, v178, v178
	v_pk_mul_f32 v[180:181], v[146:147], v[178:179] op_sel_hi:[1,0]
	v_exp_f32_e32 v170, v170
	v_exp_f32_e32 v174, v174
	v_exp_f32_e32 v171, v171
	v_exp_f32_e32 v175, v175
	v_exp_f32_e32 v172, v172
	v_exp_f32_e32 v176, v176
	v_exp_f32_e32 v173, v173
	v_exp_f32_e32 v177, v177
	v_pk_mul_f32 v[182:183], v[144:145], v[178:179] op_sel_hi:[1,0]
	v_pk_add_f32 v[144:145], v[170:171], 1.0 op_sel_hi:[1,0]
	v_pk_add_f32 v[146:147], v[172:173], 1.0 op_sel_hi:[1,0]
	v_pk_add_f32 v[150:151], v[176:177], 1.0 op_sel_hi:[1,0]
	v_pk_add_f32 v[148:149], v[174:175], 1.0 op_sel_hi:[1,0]
	v_pk_mul_f32 v[138:139], v[138:139], v[178:179] op_sel_hi:[1,0]
	v_pk_mul_f32 v[136:137], v[136:137], v[178:179] op_sel_hi:[1,0]
	v_rcp_f32_e32 v144, v144
	v_rcp_f32_e32 v148, v148
	v_rcp_f32_e32 v145, v145
	v_rcp_f32_e32 v149, v149
	v_rcp_f32_e32 v146, v146
	v_rcp_f32_e32 v150, v150
	v_rcp_f32_e32 v147, v147
	v_rcp_f32_e32 v151, v151
	s_nop 0
	v_pk_mul_f32 v[140:141], v[180:181], v[146:147]
	v_pk_mul_f32 v[142:143], v[182:183], v[144:145]
	v_pk_mul_f32 v[144:145], v[138:139], v[150:151]
	v_pk_mul_f32 v[138:139], v[136:137], v[148:149]
	v_cvt_pk_bf16_f32 v136, v142, v143
	v_cvt_pk_bf16_f32 v137, v140, v141
	v_cvt_pk_bf16_f32 v138, v138, v139
	v_cvt_pk_bf16_f32 v139, v144, v145
	v_lshl_add_u64 v[140:141], s[36:37], 0, v[82:83]
	global_store_dwordx4 v[140:141], v[136:139], off nt
	s_nop 0
	s_nop 0
	v_cvt_f32_u32_e32 v136, v87
	v_cvt_f32_u32_e32 v137, v86
	v_fmac_f32_e32 v137, 0x4f800000, v136
	v_fmamk_f32 v136, v137, 0x30000000, v234
	v_rsq_f32_e32 v144, v136
	s_nop 0
	v_mul_f32_e32 v140, 0xbfb8aa3b, v144
	v_pk_mul_f32 v[138:139], v[134:135], v[140:141] op_sel_hi:[1,0]
	v_pk_mul_f32 v[136:137], v[132:133], v[140:141] op_sel_hi:[1,0]
	v_pk_mul_f32 v[142:143], v[126:127], v[140:141] op_sel_hi:[1,0]
	v_pk_mul_f32 v[140:141], v[124:125], v[140:141] op_sel_hi:[1,0]
	v_mul_f32_e32 v144, v144, v144
	v_pk_mul_f32 v[146:147], v[130:131], v[144:145] op_sel_hi:[1,0]
	v_exp_f32_e32 v136, v136
	v_exp_f32_e32 v140, v140
	v_exp_f32_e32 v137, v137
	v_exp_f32_e32 v141, v141
	v_exp_f32_e32 v138, v138
	v_exp_f32_e32 v142, v142
	v_exp_f32_e32 v139, v139
	v_exp_f32_e32 v143, v143
	v_pk_mul_f32 v[148:149], v[128:129], v[144:145] op_sel_hi:[1,0]
	v_pk_add_f32 v[128:129], v[136:137], 1.0 op_sel_hi:[1,0]
	v_pk_add_f32 v[130:131], v[138:139], 1.0 op_sel_hi:[1,0]
	v_pk_add_f32 v[134:135], v[142:143], 1.0 op_sel_hi:[1,0]
	v_pk_add_f32 v[132:133], v[140:141], 1.0 op_sel_hi:[1,0]
	v_pk_mul_f32 v[122:123], v[122:123], v[144:145] op_sel_hi:[1,0]
	v_pk_mul_f32 v[120:121], v[120:121], v[144:145] op_sel_hi:[1,0]
	v_rcp_f32_e32 v128, v128
	v_rcp_f32_e32 v132, v132
	v_rcp_f32_e32 v129, v129
	v_rcp_f32_e32 v133, v133
	v_rcp_f32_e32 v130, v130
	v_rcp_f32_e32 v134, v134
	v_rcp_f32_e32 v131, v131
	v_rcp_f32_e32 v135, v135
	s_nop 0
	v_pk_mul_f32 v[124:125], v[146:147], v[130:131]
	v_pk_mul_f32 v[126:127], v[148:149], v[128:129]
	v_pk_mul_f32 v[128:129], v[122:123], v[134:135]
	v_pk_mul_f32 v[122:123], v[120:121], v[132:133]
	v_cvt_pk_bf16_f32 v120, v126, v127
	v_cvt_pk_bf16_f32 v121, v124, v125
	v_cvt_pk_bf16_f32 v122, v122, v123
	v_cvt_pk_bf16_f32 v123, v128, v129
	v_lshl_add_u64 v[124:125], s[4:5], 0, v[82:83]
	global_store_dwordx4 v[124:125], v[120:123], off nt
	s_or_b32 s4, s33, 0x1000
	s_add_u32 s4, s20, s4
	s_nop 0
	v_cvt_f32_u32_e32 v120, v89
	v_cvt_f32_u32_e32 v121, v88
	s_addc_u32 s5, s68, 0
	v_fmac_f32_e32 v121, 0x4f800000, v120
	v_fmamk_f32 v120, v121, 0x30000000, v234
	v_rsq_f32_e32 v128, v120
	s_nop 0
	v_mul_f32_e32 v124, 0xbfb8aa3b, v128
	v_pk_mul_f32 v[122:123], v[118:119], v[124:125] op_sel_hi:[1,0]
	v_pk_mul_f32 v[120:121], v[116:117], v[124:125] op_sel_hi:[1,0]
	v_pk_mul_f32 v[126:127], v[110:111], v[124:125] op_sel_hi:[1,0]
	v_pk_mul_f32 v[124:125], v[108:109], v[124:125] op_sel_hi:[1,0]
	v_mul_f32_e32 v128, v128, v128
	v_pk_mul_f32 v[130:131], v[114:115], v[128:129] op_sel_hi:[1,0]
	v_exp_f32_e32 v120, v120
	v_exp_f32_e32 v124, v124
	v_exp_f32_e32 v121, v121
	v_exp_f32_e32 v125, v125
	v_exp_f32_e32 v122, v122
	v_exp_f32_e32 v126, v126
	v_exp_f32_e32 v123, v123
	v_exp_f32_e32 v127, v127
	v_pk_mul_f32 v[132:133], v[112:113], v[128:129] op_sel_hi:[1,0]
	v_pk_add_f32 v[112:113], v[120:121], 1.0 op_sel_hi:[1,0]
	v_pk_add_f32 v[114:115], v[122:123], 1.0 op_sel_hi:[1,0]
	v_pk_add_f32 v[118:119], v[126:127], 1.0 op_sel_hi:[1,0]
	v_pk_add_f32 v[116:117], v[124:125], 1.0 op_sel_hi:[1,0]
	v_pk_mul_f32 v[106:107], v[106:107], v[128:129] op_sel_hi:[1,0]
	v_pk_mul_f32 v[104:105], v[104:105], v[128:129] op_sel_hi:[1,0]
	v_rcp_f32_e32 v112, v112
	v_rcp_f32_e32 v116, v116
	v_rcp_f32_e32 v113, v113
	v_rcp_f32_e32 v117, v117
	v_rcp_f32_e32 v114, v114
	v_rcp_f32_e32 v118, v118
	v_rcp_f32_e32 v115, v115
	v_rcp_f32_e32 v119, v119
	s_nop 0
	v_pk_mul_f32 v[108:109], v[130:131], v[114:115]
	v_pk_mul_f32 v[110:111], v[132:133], v[112:113]
	v_pk_mul_f32 v[112:113], v[106:107], v[118:119]
	v_pk_mul_f32 v[106:107], v[104:105], v[116:117]
	v_cvt_pk_bf16_f32 v104, v110, v111
	v_cvt_pk_bf16_f32 v105, v108, v109
	v_cvt_pk_bf16_f32 v106, v106, v107
	v_cvt_pk_bf16_f32 v107, v112, v113
	v_lshl_add_u64 v[108:109], s[4:5], 0, v[82:83]
	global_store_dwordx4 v[108:109], v[104:107], off nt
	s_or_b32 s4, s33, 0x1800
	s_add_u32 s4, s20, s4
	s_nop 0
	v_cvt_f32_u32_e32 v104, v91
	v_cvt_f32_u32_e32 v105, v90
	s_addc_u32 s5, s68, 0
	v_fmac_f32_e32 v105, 0x4f800000, v104
	v_fmamk_f32 v104, v105, 0x30000000, v234
	v_rsq_f32_e32 v112, v104
	s_nop 0
	v_mul_f32_e32 v108, 0xbfb8aa3b, v112
	v_pk_mul_f32 v[106:107], v[78:79], v[108:109] op_sel_hi:[1,0]
	v_pk_mul_f32 v[104:105], v[76:77], v[108:109] op_sel_hi:[1,0]
	v_pk_mul_f32 v[110:111], v[70:71], v[108:109] op_sel_hi:[1,0]
	v_pk_mul_f32 v[108:109], v[68:69], v[108:109] op_sel_hi:[1,0]
	v_mul_f32_e32 v112, v112, v112
	v_pk_mul_f32 v[114:115], v[74:75], v[112:113] op_sel_hi:[1,0]
	v_exp_f32_e32 v104, v104
	v_exp_f32_e32 v108, v108
	v_exp_f32_e32 v105, v105
	v_exp_f32_e32 v109, v109
	v_exp_f32_e32 v106, v106
	v_exp_f32_e32 v110, v110
	v_exp_f32_e32 v107, v107
	v_exp_f32_e32 v111, v111
	v_pk_mul_f32 v[116:117], v[72:73], v[112:113] op_sel_hi:[1,0]
	v_pk_add_f32 v[72:73], v[104:105], 1.0 op_sel_hi:[1,0]
	v_pk_add_f32 v[74:75], v[106:107], 1.0 op_sel_hi:[1,0]
	v_pk_add_f32 v[78:79], v[110:111], 1.0 op_sel_hi:[1,0]
	v_pk_add_f32 v[76:77], v[108:109], 1.0 op_sel_hi:[1,0]
	v_pk_mul_f32 v[66:67], v[66:67], v[112:113] op_sel_hi:[1,0]
	v_pk_mul_f32 v[64:65], v[64:65], v[112:113] op_sel_hi:[1,0]
	v_rcp_f32_e32 v72, v72
	v_rcp_f32_e32 v76, v76
	v_rcp_f32_e32 v73, v73
	v_rcp_f32_e32 v77, v77
	v_rcp_f32_e32 v74, v74
	v_rcp_f32_e32 v78, v78
	v_rcp_f32_e32 v75, v75
	v_rcp_f32_e32 v79, v79
	s_nop 0
	v_pk_mul_f32 v[68:69], v[114:115], v[74:75]
	v_pk_mul_f32 v[70:71], v[116:117], v[72:73]
	v_pk_mul_f32 v[72:73], v[66:67], v[78:79]
	v_pk_mul_f32 v[66:67], v[64:65], v[76:77]
	v_cvt_pk_bf16_f32 v64, v70, v71
	v_cvt_pk_bf16_f32 v65, v68, v69
	v_cvt_pk_bf16_f32 v66, v66, v67
	v_cvt_pk_bf16_f32 v67, v72, v73
	v_lshl_add_u64 v[68:69], s[4:5], 0, v[82:83]
	global_store_dwordx4 v[68:69], v[64:67], off nt
	s_add_i32 s4, s33, 0x160000
	s_add_u32 s4, s20, s4
	s_nop 0
	v_cvt_f32_u32_e32 v64, v93
	v_cvt_f32_u32_e32 v65, v92
	s_addc_u32 s5, s68, 0
	v_fmac_f32_e32 v65, 0x4f800000, v64
	v_fmamk_f32 v64, v65, 0x30000000, v234
	v_rsq_f32_e32 v72, v64
	s_nop 0
	v_mul_f32_e32 v68, 0xbfb8aa3b, v72
	v_pk_mul_f32 v[66:67], v[62:63], v[68:69] op_sel_hi:[1,0]
	v_pk_mul_f32 v[64:65], v[60:61], v[68:69] op_sel_hi:[1,0]
	v_pk_mul_f32 v[70:71], v[54:55], v[68:69] op_sel_hi:[1,0]
	v_pk_mul_f32 v[68:69], v[52:53], v[68:69] op_sel_hi:[1,0]
	v_mul_f32_e32 v72, v72, v72
	v_pk_mul_f32 v[74:75], v[58:59], v[72:73] op_sel_hi:[1,0]
	v_exp_f32_e32 v64, v64
	v_exp_f32_e32 v68, v68
	v_exp_f32_e32 v65, v65
	v_exp_f32_e32 v69, v69
	v_exp_f32_e32 v66, v66
	v_exp_f32_e32 v70, v70
	v_exp_f32_e32 v67, v67
	v_exp_f32_e32 v71, v71
	v_pk_mul_f32 v[76:77], v[56:57], v[72:73] op_sel_hi:[1,0]
	v_pk_add_f32 v[56:57], v[64:65], 1.0 op_sel_hi:[1,0]
	v_pk_add_f32 v[58:59], v[66:67], 1.0 op_sel_hi:[1,0]
	v_pk_add_f32 v[62:63], v[70:71], 1.0 op_sel_hi:[1,0]
	v_pk_add_f32 v[60:61], v[68:69], 1.0 op_sel_hi:[1,0]
	v_pk_mul_f32 v[50:51], v[50:51], v[72:73] op_sel_hi:[1,0]
	v_pk_mul_f32 v[48:49], v[48:49], v[72:73] op_sel_hi:[1,0]
	v_rcp_f32_e32 v56, v56
	v_rcp_f32_e32 v60, v60
	v_rcp_f32_e32 v57, v57
	v_rcp_f32_e32 v61, v61
	v_rcp_f32_e32 v58, v58
	v_rcp_f32_e32 v62, v62
	v_rcp_f32_e32 v59, v59
	v_rcp_f32_e32 v63, v63
	s_nop 0
	v_pk_mul_f32 v[52:53], v[74:75], v[58:59]
	v_pk_mul_f32 v[54:55], v[76:77], v[56:57]
	v_pk_mul_f32 v[56:57], v[50:51], v[62:63]
	v_pk_mul_f32 v[50:51], v[48:49], v[60:61]
	v_cvt_pk_bf16_f32 v48, v54, v55
	v_cvt_pk_bf16_f32 v49, v52, v53
	v_cvt_pk_bf16_f32 v50, v50, v51
	v_cvt_pk_bf16_f32 v51, v56, v57
	v_lshl_add_u64 v[52:53], s[4:5], 0, v[82:83]
	global_store_dwordx4 v[52:53], v[48:51], off nt
	s_add_i32 s4, s33, 0x160800
	s_add_u32 s4, s20, s4
	s_nop 0
	v_cvt_f32_u32_e32 v48, v95
	v_cvt_f32_u32_e32 v49, v94
	s_addc_u32 s5, s68, 0
	v_fmac_f32_e32 v49, 0x4f800000, v48
	v_fmamk_f32 v48, v49, 0x30000000, v234
	v_rsq_f32_e32 v56, v48
	s_nop 0
	v_mul_f32_e32 v52, 0xbfb8aa3b, v56
	v_pk_mul_f32 v[50:51], v[46:47], v[52:53] op_sel_hi:[1,0]
	v_pk_mul_f32 v[48:49], v[44:45], v[52:53] op_sel_hi:[1,0]
	v_pk_mul_f32 v[54:55], v[38:39], v[52:53] op_sel_hi:[1,0]
	v_pk_mul_f32 v[52:53], v[36:37], v[52:53] op_sel_hi:[1,0]
	v_mul_f32_e32 v56, v56, v56
	v_pk_mul_f32 v[58:59], v[42:43], v[56:57] op_sel_hi:[1,0]
	v_exp_f32_e32 v48, v48
	v_exp_f32_e32 v52, v52
	v_exp_f32_e32 v49, v49
	v_exp_f32_e32 v53, v53
	v_exp_f32_e32 v50, v50
	v_exp_f32_e32 v54, v54
	v_exp_f32_e32 v51, v51
	v_exp_f32_e32 v55, v55
	v_pk_mul_f32 v[60:61], v[40:41], v[56:57] op_sel_hi:[1,0]
	v_pk_add_f32 v[40:41], v[48:49], 1.0 op_sel_hi:[1,0]
	v_pk_add_f32 v[42:43], v[50:51], 1.0 op_sel_hi:[1,0]
	v_pk_add_f32 v[46:47], v[54:55], 1.0 op_sel_hi:[1,0]
	v_pk_add_f32 v[44:45], v[52:53], 1.0 op_sel_hi:[1,0]
	v_pk_mul_f32 v[34:35], v[34:35], v[56:57] op_sel_hi:[1,0]
	v_pk_mul_f32 v[32:33], v[32:33], v[56:57] op_sel_hi:[1,0]
	v_rcp_f32_e32 v40, v40
	v_rcp_f32_e32 v44, v44
	v_rcp_f32_e32 v41, v41
	v_rcp_f32_e32 v45, v45
	v_rcp_f32_e32 v42, v42
	v_rcp_f32_e32 v46, v46
	v_rcp_f32_e32 v43, v43
	v_rcp_f32_e32 v47, v47
	s_nop 0
	v_pk_mul_f32 v[36:37], v[58:59], v[42:43]
	v_pk_mul_f32 v[38:39], v[60:61], v[40:41]
	v_pk_mul_f32 v[40:41], v[34:35], v[46:47]
	v_pk_mul_f32 v[34:35], v[32:33], v[44:45]
	v_cvt_pk_bf16_f32 v32, v38, v39
	v_cvt_pk_bf16_f32 v33, v36, v37
	v_cvt_pk_bf16_f32 v34, v34, v35
	v_cvt_pk_bf16_f32 v35, v40, v41
	v_lshl_add_u64 v[36:37], s[4:5], 0, v[82:83]
	global_store_dwordx4 v[36:37], v[32:35], off nt
	s_add_i32 s4, s33, 0x161000
	s_add_u32 s4, s20, s4
	s_nop 0
	v_cvt_f32_u32_e32 v32, v97
	v_cvt_f32_u32_e32 v33, v96
	s_addc_u32 s5, s68, 0
	s_add_i32 s33, s33, 0x161800
	v_fmac_f32_e32 v33, 0x4f800000, v32
	v_fmamk_f32 v32, v33, 0x30000000, v234
	v_rsq_f32_e32 v40, v32
	s_nop 0
	v_mul_f32_e32 v36, 0xbfb8aa3b, v40
	v_pk_mul_f32 v[34:35], v[30:31], v[36:37] op_sel_hi:[1,0]
	v_pk_mul_f32 v[32:33], v[28:29], v[36:37] op_sel_hi:[1,0]
	v_pk_mul_f32 v[38:39], v[22:23], v[36:37] op_sel_hi:[1,0]
	v_pk_mul_f32 v[36:37], v[20:21], v[36:37] op_sel_hi:[1,0]
	v_mul_f32_e32 v40, v40, v40
	v_pk_mul_f32 v[42:43], v[26:27], v[40:41] op_sel_hi:[1,0]
	v_exp_f32_e32 v32, v32
	v_exp_f32_e32 v36, v36
	v_exp_f32_e32 v33, v33
	v_exp_f32_e32 v37, v37
	v_exp_f32_e32 v34, v34
	v_exp_f32_e32 v38, v38
	v_exp_f32_e32 v35, v35
	v_exp_f32_e32 v39, v39
	v_pk_mul_f32 v[44:45], v[24:25], v[40:41] op_sel_hi:[1,0]
	v_pk_add_f32 v[24:25], v[32:33], 1.0 op_sel_hi:[1,0]
	v_pk_add_f32 v[26:27], v[34:35], 1.0 op_sel_hi:[1,0]
	v_pk_add_f32 v[30:31], v[38:39], 1.0 op_sel_hi:[1,0]
	v_pk_add_f32 v[28:29], v[36:37], 1.0 op_sel_hi:[1,0]
	v_pk_mul_f32 v[18:19], v[18:19], v[40:41] op_sel_hi:[1,0]
	v_pk_mul_f32 v[16:17], v[16:17], v[40:41] op_sel_hi:[1,0]
	v_rcp_f32_e32 v24, v24
	v_rcp_f32_e32 v28, v28
	v_rcp_f32_e32 v25, v25
	v_rcp_f32_e32 v29, v29
	v_rcp_f32_e32 v26, v26
	v_rcp_f32_e32 v30, v30
	v_rcp_f32_e32 v27, v27
	v_rcp_f32_e32 v31, v31
	s_nop 0
	v_pk_mul_f32 v[20:21], v[42:43], v[26:27]
	v_pk_mul_f32 v[22:23], v[44:45], v[24:25]
	v_pk_mul_f32 v[24:25], v[18:19], v[30:31]
	v_pk_mul_f32 v[18:19], v[16:17], v[28:29]
	v_cvt_pk_bf16_f32 v16, v22, v23
	v_cvt_pk_bf16_f32 v17, v20, v21
	v_cvt_pk_bf16_f32 v18, v18, v19
	v_cvt_pk_bf16_f32 v19, v24, v25
	v_lshl_add_u64 v[20:21], s[4:5], 0, v[82:83]
	global_store_dwordx4 v[20:21], v[16:19], off nt
	s_add_u32 s4, s20, s33
	s_addc_u32 s5, s68, 0
	s_nop 0
	v_cvt_f32_u32_e32 v16, v99
	v_cvt_f32_u32_e32 v17, v98
	s_andn2_b64 vcc, exec, s[38:39]
	v_fmac_f32_e32 v17, 0x4f800000, v16
	v_fmamk_f32 v16, v17, 0x30000000, v234
	v_rsq_f32_e32 v24, v16
	s_nop 0
	v_mul_f32_e32 v20, 0xbfb8aa3b, v24
	v_pk_mul_f32 v[18:19], v[14:15], v[20:21] op_sel_hi:[1,0]
	v_pk_mul_f32 v[16:17], v[12:13], v[20:21] op_sel_hi:[1,0]
	v_pk_mul_f32 v[22:23], v[6:7], v[20:21] op_sel_hi:[1,0]
	v_pk_mul_f32 v[20:21], v[4:5], v[20:21] op_sel_hi:[1,0]
	v_mul_f32_e32 v24, v24, v24
	v_pk_mul_f32 v[26:27], v[10:11], v[24:25] op_sel_hi:[1,0]
	v_exp_f32_e32 v16, v16
	v_exp_f32_e32 v20, v20
	v_exp_f32_e32 v17, v17
	v_exp_f32_e32 v21, v21
	v_exp_f32_e32 v18, v18
	v_exp_f32_e32 v22, v22
	v_exp_f32_e32 v19, v19
	v_exp_f32_e32 v23, v23
	v_pk_mul_f32 v[28:29], v[8:9], v[24:25] op_sel_hi:[1,0]
	v_pk_add_f32 v[8:9], v[16:17], 1.0 op_sel_hi:[1,0]
	v_pk_add_f32 v[10:11], v[18:19], 1.0 op_sel_hi:[1,0]
	v_pk_add_f32 v[14:15], v[22:23], 1.0 op_sel_hi:[1,0]
	v_pk_add_f32 v[12:13], v[20:21], 1.0 op_sel_hi:[1,0]
	v_pk_mul_f32 v[2:3], v[2:3], v[24:25] op_sel_hi:[1,0]
	v_pk_mul_f32 v[0:1], v[0:1], v[24:25] op_sel_hi:[1,0]
	v_rcp_f32_e32 v8, v8
	v_rcp_f32_e32 v12, v12
	v_rcp_f32_e32 v9, v9
	v_rcp_f32_e32 v13, v13
	v_rcp_f32_e32 v10, v10
	v_rcp_f32_e32 v14, v14
	v_rcp_f32_e32 v11, v11
	v_rcp_f32_e32 v15, v15
	s_nop 0
	v_pk_mul_f32 v[4:5], v[26:27], v[10:11]
	v_pk_mul_f32 v[6:7], v[28:29], v[8:9]
	v_pk_mul_f32 v[8:9], v[2:3], v[14:15]
	v_pk_mul_f32 v[2:3], v[0:1], v[12:13]
	v_cvt_pk_bf16_f32 v0, v6, v7
	v_cvt_pk_bf16_f32 v1, v4, v5
	v_cvt_pk_bf16_f32 v2, v2, v3
	v_cvt_pk_bf16_f32 v3, v8, v9
	v_lshl_add_u64 v[4:5], s[4:5], 0, v[82:83]
	s_mov_b64 s[4:5], -1
	global_store_dwordx4 v[4:5], v[0:3], off nt
	s_cbranch_vccnz .LBB0_791
	s_mov_b32 s101, 0
	s_andn2_b64 vcc, exec, s[0:1]
	s_cbranch_vccnz .LBB0_790
	s_mov_b32 s101, 1
	s_branch .LBB0_790
